# mLSTM step 3: all eight fragment reads of each score tile issued up front
# baseline (speedup 1.0000x reference)
.LBB0_228:
	v_or_b32_e32 v74, s58, v73
	v_mul_u32_u24_e32 v75, 0x110, v74
	v_add3_u32 v75, 0, v75, v72
	ds_read_b128 v[64:67], v71
	ds_read_b128 v[76:79], v75 offset:17408
	ds_read_b128 v[84:87], v71 offset:64
	ds_read_b128 v[80:83], v75 offset:17472
	ds_read_b128 v[88:91], v71 offset:128
	ds_read_b128 v[92:95], v75 offset:17536
	ds_read_b128 v[156:159], v71 offset:192
	ds_read_b128 v[160:163], v75 offset:17600
	v_cmp_le_u32_e32 vcc, v74, v70
	v_lshl_add_u32 v75, v74, 2, 0
	v_add_u32_e32 v75, 0x20900, v75
	ds_read_b32 v75, v75
	s_waitcnt lgkmcnt(7)
	v_mfma_f32_16x16x32_bf16 v[64:67], v[64:67], v[76:79], 0
	s_waitcnt lgkmcnt(5)
	v_mfma_f32_16x16x32_bf16 v[64:67], v[84:87], v[80:83], v[64:67]
	s_waitcnt lgkmcnt(3)
	v_mfma_f32_16x16x32_bf16 v[64:67], v[88:91], v[92:95], v[64:67]
	s_waitcnt lgkmcnt(1)
	v_mfma_f32_16x16x32_bf16 v[64:67], v[156:159], v[160:163], v[64:67]
	v_mov_b32_e32 v76, 0
	s_and_saveexec_b64 s[12:13], vcc
	s_cbranch_execz .LBB0_230
	v_lshl_add_u32 v76, v70, 2, 0
	v_add_u32_e32 v77, 0x20800, v76
	v_add_u32_e32 v76, 0x20a00, v76
	ds_read_b32 v77, v77
	ds_read_b32 v76, v76
	s_waitcnt lgkmcnt(1)
	v_add_f32_e32 v77, v75, v77
	s_waitcnt lgkmcnt(0)
	v_sub_f32_e32 v76, v77, v76
	v_mul_f32_e32 v76, 0x3fb8aa3b, v76
	v_exp_f32_e32 v76, v76
	s_nop 0
	v_mul_f32_e32 v76, v64, v76

.LBB0_247:
	s_waitcnt lgkmcnt(0)
	v_or_b32_e32 v73, s97, v73
	v_mul_u32_u24_e32 v75, 0x110, v73
	v_add3_u32 v72, 0, v75, v72
	ds_read_b128 v[64:67], v71
	ds_read_b128 v[76:79], v72 offset:17408
	ds_read_b128 v[84:87], v71 offset:64
	ds_read_b128 v[80:83], v72 offset:17472
	ds_read_b128 v[88:91], v71 offset:128
	ds_read_b128 v[92:95], v72 offset:17536
	ds_read_b128 v[156:159], v71 offset:192
	ds_read_b128 v[160:163], v72 offset:17600
	v_cmp_le_u32_e32 vcc, v73, v70
	v_mov_b32_e32 v75, 0
	v_lshl_add_u32 v71, v73, 2, 0
	v_add_u32_e32 v71, 0x20900, v71
	ds_read_b32 v71, v71
	s_waitcnt lgkmcnt(7)
	v_mfma_f32_16x16x32_bf16 v[64:67], v[64:67], v[76:79], 0
	s_waitcnt lgkmcnt(5)
	v_mfma_f32_16x16x32_bf16 v[64:67], v[84:87], v[80:83], v[64:67]
	s_waitcnt lgkmcnt(3)
	v_mfma_f32_16x16x32_bf16 v[64:67], v[88:91], v[92:95], v[64:67]
	s_waitcnt lgkmcnt(1)
	v_mfma_f32_16x16x32_bf16 v[64:67], v[156:159], v[160:163], v[64:67]
	v_lshl_add_u32 v72, v70, 2, 0
	s_and_saveexec_b64 s[12:13], vcc
	s_cbranch_execz .LBB0_249
	v_add_u32_e32 v75, 0x20800, v72
	v_add_u32_e32 v76, 0x20a00, v72
	ds_read_b32 v75, v75
	ds_read_b32 v76, v76
	s_waitcnt lgkmcnt(1)
	v_add_f32_e32 v75, v71, v75
	s_waitcnt lgkmcnt(0)
	v_sub_f32_e32 v75, v75, v76
	v_mul_f32_e32 v75, 0x3fb8aa3b, v75
	v_exp_f32_e32 v75, v75
	s_nop 0
	v_mul_f32_e32 v75, v64, v75
